# phase 10 latent-row ff2 GEMM hand-written on v_mfma_f32_32x32x16_bf16 (128x256 tile per workgroup, LDS swizzle (row>>1)&7), replacing the 16x16x32 loop
# baseline (speedup 1.0000x reference)
.LBB0_1063:
	s_cmpk_gt_u32 s74, 0x1ff
	s_cbranch_scc1 .Lff2a_done
	s_and_b32 s6, s74, 7
	s_lshr_b32 s7, s74, 3
	s_lshl_b32 s6, s6, 4
	s_lshr_b32 s8, s7, 2
	s_add_u32 s6, s6, s8
	s_and_b32 s7, s7, 3
	s_lshr_b32 s8, s6, 6
	s_and_b32 s9, s6, 63
	s_mul_i32 s10, s8, 0x42
	s_add_u32 s10, s10, s9
	s_add_u32 s10, s10, 2
	v_lshrrev_b32_e32 v132, 6, v144
	v_and_b32_e32 v133, 63, v144
	v_readfirstlane_b32 s11, v132
	v_and_b32_e32 v134, 31, v133
	v_lshrrev_b32_e32 v135, 5, v133
	v_lshrrev_b32_e32 v136, 3, v133
	v_and_b32_e32 v137, 7, v133
	s_lshl_b32 s12, s10, 7
	s_lshl_b32 s13, s11, 5
	s_add_u32 s12, s12, s13
	s_mul_i32 s13, s12, 0x2080
	s_add_u32 s44, s94, s13
	s_addc_u32 s45, s95, 0
	s_add_u32 s44, s44, 0x4510000
	s_addc_u32 s45, s45, 0
	v_mul_u32_u24_e32 v236, 0x2080, v134
	v_lshl_add_u32 v236, v135, 4, v236
	s_lshl_b32 s12, s7, 8
	s_lshl_b32 s13, s11, 3
	s_add_u32 s12, s12, s13
	s_mul_i32 s13, s12, 0x2080
	s_add_u32 s46, s94, s13
	s_addc_u32 s47, s95, 0
	s_add_u32 s46, s46, 0x1910000
	s_addc_u32 s47, s47, 0
	s_and_b32 s12, s11, 1
	s_lshl_b32 s12, s12, 2
	v_lshrrev_b32_e32 v138, 1, v136
	v_or_b32_e32 v138, s12, v138
	v_xor_b32_e32 v138, v137, v138
	v_mul_u32_u24_e32 v228, 0x2080, v136
	v_lshl_add_u32 v228, v138, 4, v228
	v_add_u32_e32 v229, 0x41000, v228
	v_add_u32_e32 v230, 0x82000, v228
	v_add_u32_e32 v231, 0xc3000, v228
	v_add_u32_e32 v232, 0x104000, v228
	v_add_u32_e32 v233, 0x145000, v228
	v_add_u32_e32 v234, 0x186000, v228
	v_add_u32_e32 v235, 0x1c7000, v228
	v_bfe_u32 v138, v134, 1, 3
	v_xor_b32_e32 v138, v138, v135
	v_lshlrev_b32_e32 v238, 7, v134
	v_lshl_add_u32 v238, v138, 4, v238
	v_xor_b32_e32 v239, 0x20, v238
	v_xor_b32_e32 v240, 0x40, v238
	v_xor_b32_e32 v241, 0x60, v238
	s_lshl_b32 s50, s11, 10
	s_movk_i32 s51, 0x20
	s_lshl_b32 s12, s6, 7
	s_lshl_b32 s13, s11, 5
	s_add_u32 s12, s12, s13
	s_lshl_b32 s12, s12, 12
	s_lshl_b32 s13, s7, 10
	s_add_u32 s12, s12, s13
	s_add_u32 s52, s92, s12
	s_addc_u32 s53, s93, 0
	s_mul_i32 s12, s8, 0x6000
	s_add_u32 s12, s12, s13
	s_add_u32 s12, s12, 0x5000
	s_add_u32 s54, s94, s12
	s_addc_u32 s55, s95, 0
	s_mov_b32 m0, s50
	s_nop 0
	global_load_lds_dwordx4 v228, s[46:47]
	s_add_u32 m0, s50, 0x1000
	s_nop 0
	global_load_lds_dwordx4 v229, s[46:47]
	s_add_u32 m0, s50, 0x2000
	s_nop 0
	global_load_lds_dwordx4 v230, s[46:47]
	s_add_u32 m0, s50, 0x3000
	s_nop 0
	global_load_lds_dwordx4 v231, s[46:47]
	s_add_u32 m0, s50, 0x4000
	s_nop 0
	global_load_lds_dwordx4 v232, s[46:47]
	s_add_u32 m0, s50, 0x5000
	s_nop 0
	global_load_lds_dwordx4 v233, s[46:47]
	s_add_u32 m0, s50, 0x6000
	s_nop 0
	global_load_lds_dwordx4 v234, s[46:47]
	s_add_u32 m0, s50, 0x7000
	s_nop 0
	global_load_lds_dwordx4 v235, s[46:47]
	global_load_dwordx4 v[148:151], v236, s[44:45]
	global_load_dwordx4 v[152:155], v236, s[44:45] offset:32
	global_load_dwordx4 v[156:159], v236, s[44:45] offset:64
	global_load_dwordx4 v[160:163], v236, s[44:45] offset:96
	s_add_u32 s44, s44, 0x80
	s_addc_u32 s45, s45, 0
	s_add_u32 s46, s46, 0x80
	s_addc_u32 s47, s47, 0
	v_mov_b32_e32 v4, 0
	v_mov_b32_e32 v5, 0
	v_mov_b32_e32 v6, 0
	v_mov_b32_e32 v7, 0
	v_mov_b32_e32 v8, 0
	v_mov_b32_e32 v9, 0
	v_mov_b32_e32 v10, 0
	v_mov_b32_e32 v11, 0
	v_mov_b32_e32 v12, 0
	v_mov_b32_e32 v13, 0
	v_mov_b32_e32 v14, 0
	v_mov_b32_e32 v15, 0
	v_mov_b32_e32 v16, 0
	v_mov_b32_e32 v17, 0
	v_mov_b32_e32 v18, 0
	v_mov_b32_e32 v19, 0
	v_mov_b32_e32 v20, 0
	v_mov_b32_e32 v21, 0
	v_mov_b32_e32 v22, 0
	v_mov_b32_e32 v23, 0
	v_mov_b32_e32 v24, 0
	v_mov_b32_e32 v25, 0
	v_mov_b32_e32 v26, 0
	v_mov_b32_e32 v27, 0
	v_mov_b32_e32 v28, 0
	v_mov_b32_e32 v29, 0
	v_mov_b32_e32 v30, 0
	v_mov_b32_e32 v31, 0
	v_mov_b32_e32 v32, 0
	v_mov_b32_e32 v33, 0
	v_mov_b32_e32 v34, 0
	v_mov_b32_e32 v35, 0
	v_mov_b32_e32 v36, 0
	v_mov_b32_e32 v37, 0
	v_mov_b32_e32 v38, 0
	v_mov_b32_e32 v39, 0
	v_mov_b32_e32 v40, 0
	v_mov_b32_e32 v41, 0
	v_mov_b32_e32 v42, 0
	v_mov_b32_e32 v43, 0
	v_mov_b32_e32 v44, 0
	v_mov_b32_e32 v45, 0
	v_mov_b32_e32 v46, 0
	v_mov_b32_e32 v47, 0
	v_mov_b32_e32 v48, 0
	v_mov_b32_e32 v49, 0
	v_mov_b32_e32 v50, 0
	v_mov_b32_e32 v51, 0
	v_mov_b32_e32 v52, 0
	v_mov_b32_e32 v53, 0
	v_mov_b32_e32 v54, 0
	v_mov_b32_e32 v55, 0
	v_mov_b32_e32 v56, 0
	v_mov_b32_e32 v57, 0
	v_mov_b32_e32 v58, 0
	v_mov_b32_e32 v59, 0
	v_mov_b32_e32 v60, 0
	v_mov_b32_e32 v61, 0
	v_mov_b32_e32 v62, 0
	v_mov_b32_e32 v63, 0
	v_mov_b32_e32 v64, 0
	v_mov_b32_e32 v65, 0
	v_mov_b32_e32 v66, 0
	v_mov_b32_e32 v67, 0
	v_mov_b32_e32 v68, 0
	v_mov_b32_e32 v69, 0
	v_mov_b32_e32 v70, 0
	v_mov_b32_e32 v71, 0
	v_mov_b32_e32 v72, 0
	v_mov_b32_e32 v73, 0
	v_mov_b32_e32 v74, 0
	v_mov_b32_e32 v75, 0
	v_mov_b32_e32 v76, 0
	v_mov_b32_e32 v77, 0
	v_mov_b32_e32 v78, 0
	v_mov_b32_e32 v79, 0
	v_mov_b32_e32 v80, 0
	v_mov_b32_e32 v81, 0
	v_mov_b32_e32 v82, 0
	v_mov_b32_e32 v83, 0
	v_mov_b32_e32 v84, 0
	v_mov_b32_e32 v85, 0
	v_mov_b32_e32 v86, 0
	v_mov_b32_e32 v87, 0
	v_mov_b32_e32 v88, 0
	v_mov_b32_e32 v89, 0
	v_mov_b32_e32 v90, 0
	v_mov_b32_e32 v91, 0
	v_mov_b32_e32 v92, 0
	v_mov_b32_e32 v93, 0
	v_mov_b32_e32 v94, 0
	v_mov_b32_e32 v95, 0
	v_mov_b32_e32 v96, 0
	v_mov_b32_e32 v97, 0
	v_mov_b32_e32 v98, 0
	v_mov_b32_e32 v99, 0
	v_mov_b32_e32 v100, 0
	v_mov_b32_e32 v101, 0
	v_mov_b32_e32 v102, 0
	v_mov_b32_e32 v103, 0
	v_mov_b32_e32 v104, 0
	v_mov_b32_e32 v105, 0
	v_mov_b32_e32 v106, 0
	v_mov_b32_e32 v107, 0
	v_mov_b32_e32 v108, 0
	v_mov_b32_e32 v109, 0
	v_mov_b32_e32 v110, 0
	v_mov_b32_e32 v111, 0
	v_mov_b32_e32 v112, 0
	v_mov_b32_e32 v113, 0
	v_mov_b32_e32 v114, 0
	v_mov_b32_e32 v115, 0
	v_mov_b32_e32 v116, 0
	v_mov_b32_e32 v117, 0
	v_mov_b32_e32 v118, 0
	v_mov_b32_e32 v119, 0
	v_mov_b32_e32 v120, 0
	v_mov_b32_e32 v121, 0
	v_mov_b32_e32 v122, 0
	v_mov_b32_e32 v123, 0
	v_mov_b32_e32 v124, 0
	v_mov_b32_e32 v125, 0
	v_mov_b32_e32 v126, 0
	v_mov_b32_e32 v127, 0
	v_mov_b32_e32 v128, 0
	v_mov_b32_e32 v129, 0
	v_mov_b32_e32 v130, 0
	v_mov_b32_e32 v131, 0
.Lff2a_loop:
	s_waitcnt vmcnt(0)
	s_barrier
	s_add_u32 m0, s50, 0x8000
	ds_read_b128 v[180:183], v238 offset:0
	global_load_lds_dwordx4 v228, s[46:47]
	s_add_u32 m0, s50, 0x9000
	ds_read_b128 v[184:187], v238 offset:4096
	global_load_lds_dwordx4 v229, s[46:47]
	s_add_u32 m0, s50, 0xa000
	ds_read_b128 v[188:191], v238 offset:8192
	global_load_lds_dwordx4 v230, s[46:47]
	s_add_u32 m0, s50, 0xb000
	ds_read_b128 v[192:195], v238 offset:12288
	global_load_lds_dwordx4 v231, s[46:47]
	s_add_u32 m0, s50, 0xc000
	ds_read_b128 v[196:199], v238 offset:16384
	global_load_lds_dwordx4 v232, s[46:47]
	s_add_u32 m0, s50, 0xd000
	ds_read_b128 v[200:203], v238 offset:20480
	global_load_lds_dwordx4 v233, s[46:47]
	s_add_u32 m0, s50, 0xe000
	ds_read_b128 v[204:207], v238 offset:24576
	global_load_lds_dwordx4 v234, s[46:47]
	s_add_u32 m0, s50, 0xf000
	ds_read_b128 v[208:211], v238 offset:28672
	global_load_lds_dwordx4 v235, s[46:47]
	global_load_dwordx4 v[164:167], v236, s[44:45]
	global_load_dwordx4 v[168:171], v236, s[44:45] offset:32
	global_load_dwordx4 v[172:175], v236, s[44:45] offset:64
	global_load_dwordx4 v[176:179], v236, s[44:45] offset:96
	s_add_u32 s44, s44, 0x80
	s_addc_u32 s45, s45, 0
	s_add_u32 s46, s46, 0x80
	s_addc_u32 s47, s47, 0
	ds_read_b128 v[212:215], v239 offset:0
	ds_read_b128 v[216:219], v239 offset:4096
	ds_read_b128 v[220:223], v239 offset:8192
	ds_read_b128 v[224:227], v239 offset:12288
	s_waitcnt lgkmcnt(11)
	v_mfma_f32_32x32x16_bf16 v[4:19], v[180:183], v[148:151], v[4:19]
	ds_read_b128 v[180:183], v239 offset:16384
	s_waitcnt lgkmcnt(11)
	v_mfma_f32_32x32x16_bf16 v[20:35], v[184:187], v[148:151], v[20:35]
	ds_read_b128 v[184:187], v239 offset:20480
	s_waitcnt lgkmcnt(11)
	v_mfma_f32_32x32x16_bf16 v[36:51], v[188:191], v[148:151], v[36:51]
	ds_read_b128 v[188:191], v239 offset:24576
	s_waitcnt lgkmcnt(11)
	v_mfma_f32_32x32x16_bf16 v[52:67], v[192:195], v[148:151], v[52:67]
	ds_read_b128 v[192:195], v239 offset:28672
	s_waitcnt lgkmcnt(11)
	v_mfma_f32_32x32x16_bf16 v[68:83], v[196:199], v[148:151], v[68:83]
	ds_read_b128 v[196:199], v240 offset:0
	s_waitcnt lgkmcnt(11)
	v_mfma_f32_32x32x16_bf16 v[84:99], v[200:203], v[148:151], v[84:99]
	ds_read_b128 v[200:203], v240 offset:4096
	s_waitcnt lgkmcnt(11)
	v_mfma_f32_32x32x16_bf16 v[100:115], v[204:207], v[148:151], v[100:115]
	ds_read_b128 v[204:207], v240 offset:8192
	s_waitcnt lgkmcnt(11)
	v_mfma_f32_32x32x16_bf16 v[116:131], v[208:211], v[148:151], v[116:131]
	ds_read_b128 v[208:211], v240 offset:12288
	s_waitcnt lgkmcnt(11)
	v_mfma_f32_32x32x16_bf16 v[4:19], v[212:215], v[152:155], v[4:19]
	ds_read_b128 v[212:215], v240 offset:16384
	s_waitcnt lgkmcnt(11)
	v_mfma_f32_32x32x16_bf16 v[20:35], v[216:219], v[152:155], v[20:35]
	ds_read_b128 v[216:219], v240 offset:20480
	s_waitcnt lgkmcnt(11)
	v_mfma_f32_32x32x16_bf16 v[36:51], v[220:223], v[152:155], v[36:51]
	ds_read_b128 v[220:223], v240 offset:24576
	s_waitcnt lgkmcnt(11)
	v_mfma_f32_32x32x16_bf16 v[52:67], v[224:227], v[152:155], v[52:67]
	ds_read_b128 v[224:227], v240 offset:28672
	s_waitcnt lgkmcnt(11)
	v_mfma_f32_32x32x16_bf16 v[68:83], v[180:183], v[152:155], v[68:83]
	ds_read_b128 v[180:183], v241 offset:0
	s_waitcnt lgkmcnt(11)
	v_mfma_f32_32x32x16_bf16 v[84:99], v[184:187], v[152:155], v[84:99]
	ds_read_b128 v[184:187], v241 offset:4096
	s_waitcnt lgkmcnt(11)
	v_mfma_f32_32x32x16_bf16 v[100:115], v[188:191], v[152:155], v[100:115]
	ds_read_b128 v[188:191], v241 offset:8192
	s_waitcnt lgkmcnt(11)
	v_mfma_f32_32x32x16_bf16 v[116:131], v[192:195], v[152:155], v[116:131]
	ds_read_b128 v[192:195], v241 offset:12288
	s_waitcnt lgkmcnt(11)
	v_mfma_f32_32x32x16_bf16 v[4:19], v[196:199], v[156:159], v[4:19]
	ds_read_b128 v[196:199], v241 offset:16384
	s_waitcnt lgkmcnt(11)
	v_mfma_f32_32x32x16_bf16 v[20:35], v[200:203], v[156:159], v[20:35]
	ds_read_b128 v[200:203], v241 offset:20480
	s_waitcnt lgkmcnt(11)
	v_mfma_f32_32x32x16_bf16 v[36:51], v[204:207], v[156:159], v[36:51]
	ds_read_b128 v[204:207], v241 offset:24576
	s_waitcnt lgkmcnt(11)
	v_mfma_f32_32x32x16_bf16 v[52:67], v[208:211], v[156:159], v[52:67]
	ds_read_b128 v[208:211], v241 offset:28672
	s_waitcnt lgkmcnt(11)
	v_mfma_f32_32x32x16_bf16 v[68:83], v[212:215], v[156:159], v[68:83]
	s_waitcnt lgkmcnt(10)
	v_mfma_f32_32x32x16_bf16 v[84:99], v[216:219], v[156:159], v[84:99]
	s_waitcnt lgkmcnt(9)
	v_mfma_f32_32x32x16_bf16 v[100:115], v[220:223], v[156:159], v[100:115]
	s_waitcnt lgkmcnt(8)
	v_mfma_f32_32x32x16_bf16 v[116:131], v[224:227], v[156:159], v[116:131]
	s_waitcnt lgkmcnt(7)
	v_mfma_f32_32x32x16_bf16 v[4:19], v[180:183], v[160:163], v[4:19]
	s_waitcnt lgkmcnt(6)
	v_mfma_f32_32x32x16_bf16 v[20:35], v[184:187], v[160:163], v[20:35]
	s_waitcnt lgkmcnt(5)
	v_mfma_f32_32x32x16_bf16 v[36:51], v[188:191], v[160:163], v[36:51]
	s_waitcnt lgkmcnt(4)
	v_mfma_f32_32x32x16_bf16 v[52:67], v[192:195], v[160:163], v[52:67]
	s_waitcnt lgkmcnt(3)
	v_mfma_f32_32x32x16_bf16 v[68:83], v[196:199], v[160:163], v[68:83]
	s_waitcnt lgkmcnt(2)
	v_mfma_f32_32x32x16_bf16 v[84:99], v[200:203], v[160:163], v[84:99]
	s_waitcnt lgkmcnt(1)
	v_mfma_f32_32x32x16_bf16 v[100:115], v[204:207], v[160:163], v[100:115]
	s_waitcnt lgkmcnt(0)
	v_mfma_f32_32x32x16_bf16 v[116:131], v[208:211], v[160:163], v[116:131]
	s_waitcnt vmcnt(0)
	s_barrier
	ds_read_b128 v[180:183], v238 offset:32768
	ds_read_b128 v[184:187], v238 offset:36864
	ds_read_b128 v[188:191], v238 offset:40960
	ds_read_b128 v[192:195], v238 offset:45056
	ds_read_b128 v[196:199], v238 offset:49152
	ds_read_b128 v[200:203], v238 offset:53248
	ds_read_b128 v[204:207], v238 offset:57344
	ds_read_b128 v[208:211], v238 offset:61440
	ds_read_b128 v[212:215], v239 offset:32768
	ds_read_b128 v[216:219], v239 offset:36864
	ds_read_b128 v[220:223], v239 offset:40960
	ds_read_b128 v[224:227], v239 offset:45056
	s_cmp_eq_u32 s51, 1
	s_cbranch_scc1 .Lff2a_last
	s_mov_b32 m0, s50
	s_nop 0
	global_load_lds_dwordx4 v228, s[46:47]
	s_add_u32 m0, s50, 0x1000
	s_nop 0
	global_load_lds_dwordx4 v229, s[46:47]
	s_add_u32 m0, s50, 0x2000
	s_nop 0
	global_load_lds_dwordx4 v230, s[46:47]
	s_add_u32 m0, s50, 0x3000
	s_nop 0
	global_load_lds_dwordx4 v231, s[46:47]
	s_add_u32 m0, s50, 0x4000
	s_nop 0
	global_load_lds_dwordx4 v232, s[46:47]
	s_add_u32 m0, s50, 0x5000
	s_nop 0
	global_load_lds_dwordx4 v233, s[46:47]
	s_add_u32 m0, s50, 0x6000
	s_nop 0
	global_load_lds_dwordx4 v234, s[46:47]
	s_add_u32 m0, s50, 0x7000
	s_nop 0
	global_load_lds_dwordx4 v235, s[46:47]
	global_load_dwordx4 v[148:151], v236, s[44:45]
	global_load_dwordx4 v[152:155], v236, s[44:45] offset:32
	global_load_dwordx4 v[156:159], v236, s[44:45] offset:64
	global_load_dwordx4 v[160:163], v236, s[44:45] offset:96
	s_add_u32 s44, s44, 0x80
	s_addc_u32 s45, s45, 0
	s_add_u32 s46, s46, 0x80
	s_addc_u32 s47, s47, 0
.Lff2a_last:
	s_waitcnt lgkmcnt(11)
	v_mfma_f32_32x32x16_bf16 v[4:19], v[180:183], v[164:167], v[4:19]
	ds_read_b128 v[180:183], v239 offset:49152
	s_waitcnt lgkmcnt(11)
	v_mfma_f32_32x32x16_bf16 v[20:35], v[184:187], v[164:167], v[20:35]
	ds_read_b128 v[184:187], v239 offset:53248
	s_waitcnt lgkmcnt(11)
	v_mfma_f32_32x32x16_bf16 v[36:51], v[188:191], v[164:167], v[36:51]
	ds_read_b128 v[188:191], v239 offset:57344
	s_waitcnt lgkmcnt(11)
	v_mfma_f32_32x32x16_bf16 v[52:67], v[192:195], v[164:167], v[52:67]
	ds_read_b128 v[192:195], v239 offset:61440
	s_waitcnt lgkmcnt(11)
	v_mfma_f32_32x32x16_bf16 v[68:83], v[196:199], v[164:167], v[68:83]
	ds_read_b128 v[196:199], v240 offset:32768
	s_waitcnt lgkmcnt(11)
	v_mfma_f32_32x32x16_bf16 v[84:99], v[200:203], v[164:167], v[84:99]
	ds_read_b128 v[200:203], v240 offset:36864
	s_waitcnt lgkmcnt(11)
	v_mfma_f32_32x32x16_bf16 v[100:115], v[204:207], v[164:167], v[100:115]
	ds_read_b128 v[204:207], v240 offset:40960
	s_waitcnt lgkmcnt(11)
	v_mfma_f32_32x32x16_bf16 v[116:131], v[208:211], v[164:167], v[116:131]
	ds_read_b128 v[208:211], v240 offset:45056
	s_waitcnt lgkmcnt(11)
	v_mfma_f32_32x32x16_bf16 v[4:19], v[212:215], v[168:171], v[4:19]
	ds_read_b128 v[212:215], v240 offset:49152
	s_waitcnt lgkmcnt(11)
	v_mfma_f32_32x32x16_bf16 v[20:35], v[216:219], v[168:171], v[20:35]
	ds_read_b128 v[216:219], v240 offset:53248
	s_waitcnt lgkmcnt(11)
	v_mfma_f32_32x32x16_bf16 v[36:51], v[220:223], v[168:171], v[36:51]
	ds_read_b128 v[220:223], v240 offset:57344
	s_waitcnt lgkmcnt(11)
	v_mfma_f32_32x32x16_bf16 v[52:67], v[224:227], v[168:171], v[52:67]
	ds_read_b128 v[224:227], v240 offset:61440
	s_waitcnt lgkmcnt(11)
	v_mfma_f32_32x32x16_bf16 v[68:83], v[180:183], v[168:171], v[68:83]
	ds_read_b128 v[180:183], v241 offset:32768
	s_waitcnt lgkmcnt(11)
	v_mfma_f32_32x32x16_bf16 v[84:99], v[184:187], v[168:171], v[84:99]
	ds_read_b128 v[184:187], v241 offset:36864
	s_waitcnt lgkmcnt(11)
	v_mfma_f32_32x32x16_bf16 v[100:115], v[188:191], v[168:171], v[100:115]
	ds_read_b128 v[188:191], v241 offset:40960
	s_waitcnt lgkmcnt(11)
	v_mfma_f32_32x32x16_bf16 v[116:131], v[192:195], v[168:171], v[116:131]
	ds_read_b128 v[192:195], v241 offset:45056
	s_waitcnt lgkmcnt(11)
	v_mfma_f32_32x32x16_bf16 v[4:19], v[196:199], v[172:175], v[4:19]
	ds_read_b128 v[196:199], v241 offset:49152
	s_waitcnt lgkmcnt(11)
	v_mfma_f32_32x32x16_bf16 v[20:35], v[200:203], v[172:175], v[20:35]
	ds_read_b128 v[200:203], v241 offset:53248
	s_waitcnt lgkmcnt(11)
	v_mfma_f32_32x32x16_bf16 v[36:51], v[204:207], v[172:175], v[36:51]
	ds_read_b128 v[204:207], v241 offset:57344
	s_waitcnt lgkmcnt(11)
	v_mfma_f32_32x32x16_bf16 v[52:67], v[208:211], v[172:175], v[52:67]
	ds_read_b128 v[208:211], v241 offset:61440
	s_waitcnt lgkmcnt(11)
	v_mfma_f32_32x32x16_bf16 v[68:83], v[212:215], v[172:175], v[68:83]
	s_waitcnt lgkmcnt(10)
	v_mfma_f32_32x32x16_bf16 v[84:99], v[216:219], v[172:175], v[84:99]
	s_waitcnt lgkmcnt(9)
	v_mfma_f32_32x32x16_bf16 v[100:115], v[220:223], v[172:175], v[100:115]
	s_waitcnt lgkmcnt(8)
	v_mfma_f32_32x32x16_bf16 v[116:131], v[224:227], v[172:175], v[116:131]
	s_waitcnt lgkmcnt(7)
	v_mfma_f32_32x32x16_bf16 v[4:19], v[180:183], v[176:179], v[4:19]
	s_waitcnt lgkmcnt(6)
	v_mfma_f32_32x32x16_bf16 v[20:35], v[184:187], v[176:179], v[20:35]
	s_waitcnt lgkmcnt(5)
	v_mfma_f32_32x32x16_bf16 v[36:51], v[188:191], v[176:179], v[36:51]
	s_waitcnt lgkmcnt(4)
	v_mfma_f32_32x32x16_bf16 v[52:67], v[192:195], v[176:179], v[52:67]
	s_waitcnt lgkmcnt(3)
	v_mfma_f32_32x32x16_bf16 v[68:83], v[196:199], v[176:179], v[68:83]
	s_waitcnt lgkmcnt(2)
	v_mfma_f32_32x32x16_bf16 v[84:99], v[200:203], v[176:179], v[84:99]
	s_waitcnt lgkmcnt(1)
	v_mfma_f32_32x32x16_bf16 v[100:115], v[204:207], v[176:179], v[100:115]
	s_waitcnt lgkmcnt(0)
	v_mfma_f32_32x32x16_bf16 v[116:131], v[208:211], v[176:179], v[116:131]
	s_sub_u32 s51, s51, 1
	s_cmp_lg_u32 s51, 0
	s_cbranch_scc1 .Lff2a_loop
	s_nop 7
	s_nop 7
	v_lshlrev_b32_e32 v246, 4, v135
	v_lshl_add_u32 v244, v134, 12, v246
	global_load_dwordx4 v[148:151], v246, s[54:55]
	global_load_dwordx4 v[152:155], v246, s[54:55] offset:32
	global_load_dwordx4 v[156:159], v246, s[54:55] offset:64
	global_load_dwordx4 v[160:163], v246, s[54:55] offset:96
	global_load_dwordx4 v[164:167], v246, s[54:55] offset:128
	global_load_dwordx4 v[168:171], v246, s[54:55] offset:160
	global_load_dwordx4 v[172:175], v246, s[54:55] offset:192
	global_load_dwordx4 v[176:179], v246, s[54:55] offset:224
	global_load_dwordx4 v[180:183], v246, s[54:55] offset:256
	global_load_dwordx4 v[184:187], v246, s[54:55] offset:288
	global_load_dwordx4 v[188:191], v246, s[54:55] offset:320
	global_load_dwordx4 v[192:195], v246, s[54:55] offset:352
	global_load_dwordx4 v[196:199], v246, s[54:55] offset:384
	global_load_dwordx4 v[200:203], v246, s[54:55] offset:416
	global_load_dwordx4 v[204:207], v246, s[54:55] offset:448
	global_load_dwordx4 v[208:211], v246, s[54:55] offset:480
	global_load_dwordx4 v[212:215], v244, s[52:53]
	global_load_dwordx4 v[216:219], v244, s[52:53] offset:32
	global_load_dwordx4 v[220:223], v244, s[52:53] offset:64
	global_load_dwordx4 v[224:227], v244, s[52:53] offset:96
	global_load_dwordx4 v[228:231], v244, s[52:53] offset:128
	global_load_dwordx4 v[232:235], v244, s[52:53] offset:160
	global_load_dwordx4 v[236:239], v244, s[52:53] offset:192
	global_load_dwordx4 v[240:243], v244, s[52:53] offset:224
	s_waitcnt vmcnt(4)
	v_fmac_f32_e32 v212, v148, v4
	v_fmac_f32_e32 v213, v149, v5
	v_fmac_f32_e32 v214, v150, v6
	v_fmac_f32_e32 v215, v151, v7
	v_fmac_f32_e32 v216, v152, v8
	v_fmac_f32_e32 v217, v153, v9
	v_fmac_f32_e32 v218, v154, v10
	v_fmac_f32_e32 v219, v155, v11
	v_fmac_f32_e32 v220, v156, v12
	v_fmac_f32_e32 v221, v157, v13
	v_fmac_f32_e32 v222, v158, v14
	v_fmac_f32_e32 v223, v159, v15
	v_fmac_f32_e32 v224, v160, v16
	v_fmac_f32_e32 v225, v161, v17
	v_fmac_f32_e32 v226, v162, v18
	v_fmac_f32_e32 v227, v163, v19
	global_store_dwordx4 v244, v[212:215], s[52:53]
	global_store_dwordx4 v244, v[216:219], s[52:53] offset:32
	global_store_dwordx4 v244, v[220:223], s[52:53] offset:64
	global_store_dwordx4 v244, v[224:227], s[52:53] offset:96
	global_load_dwordx4 v[212:215], v244, s[52:53] offset:256
	global_load_dwordx4 v[216:219], v244, s[52:53] offset:288
	global_load_dwordx4 v[220:223], v244, s[52:53] offset:320
	global_load_dwordx4 v[224:227], v244, s[52:53] offset:352
	s_waitcnt vmcnt(4)
	v_fmac_f32_e32 v228, v164, v20
	v_fmac_f32_e32 v229, v165, v21
	v_fmac_f32_e32 v230, v166, v22
	v_fmac_f32_e32 v231, v167, v23
	v_fmac_f32_e32 v232, v168, v24
	v_fmac_f32_e32 v233, v169, v25
	v_fmac_f32_e32 v234, v170, v26
	v_fmac_f32_e32 v235, v171, v27
	v_fmac_f32_e32 v236, v172, v28
	v_fmac_f32_e32 v237, v173, v29
	v_fmac_f32_e32 v238, v174, v30
	v_fmac_f32_e32 v239, v175, v31
	v_fmac_f32_e32 v240, v176, v32
	v_fmac_f32_e32 v241, v177, v33
	v_fmac_f32_e32 v242, v178, v34
	v_fmac_f32_e32 v243, v179, v35
	global_store_dwordx4 v244, v[228:231], s[52:53] offset:128
	global_store_dwordx4 v244, v[232:235], s[52:53] offset:160
	global_store_dwordx4 v244, v[236:239], s[52:53] offset:192
	global_store_dwordx4 v244, v[240:243], s[52:53] offset:224
	global_load_dwordx4 v[228:231], v244, s[52:53] offset:384
	global_load_dwordx4 v[232:235], v244, s[52:53] offset:416
	global_load_dwordx4 v[236:239], v244, s[52:53] offset:448
	global_load_dwordx4 v[240:243], v244, s[52:53] offset:480
	s_waitcnt vmcnt(4)
	v_fmac_f32_e32 v212, v180, v36
	v_fmac_f32_e32 v213, v181, v37
	v_fmac_f32_e32 v214, v182, v38
	v_fmac_f32_e32 v215, v183, v39
	v_fmac_f32_e32 v216, v184, v40
	v_fmac_f32_e32 v217, v185, v41
	v_fmac_f32_e32 v218, v186, v42
	v_fmac_f32_e32 v219, v187, v43
	v_fmac_f32_e32 v220, v188, v44
	v_fmac_f32_e32 v221, v189, v45
	v_fmac_f32_e32 v222, v190, v46
	v_fmac_f32_e32 v223, v191, v47
	v_fmac_f32_e32 v224, v192, v48
	v_fmac_f32_e32 v225, v193, v49
	v_fmac_f32_e32 v226, v194, v50
	v_fmac_f32_e32 v227, v195, v51
	global_store_dwordx4 v244, v[212:215], s[52:53] offset:256
	global_store_dwordx4 v244, v[216:219], s[52:53] offset:288
	global_store_dwordx4 v244, v[220:223], s[52:53] offset:320
	global_store_dwordx4 v244, v[224:227], s[52:53] offset:352
	s_waitcnt vmcnt(0)
	v_fmac_f32_e32 v228, v196, v52
	v_fmac_f32_e32 v229, v197, v53
	v_fmac_f32_e32 v230, v198, v54
	v_fmac_f32_e32 v231, v199, v55
	v_fmac_f32_e32 v232, v200, v56
	v_fmac_f32_e32 v233, v201, v57
	v_fmac_f32_e32 v234, v202, v58
	v_fmac_f32_e32 v235, v203, v59
	v_fmac_f32_e32 v236, v204, v60
	v_fmac_f32_e32 v237, v205, v61
	v_fmac_f32_e32 v238, v206, v62
	v_fmac_f32_e32 v239, v207, v63
	v_fmac_f32_e32 v240, v208, v64
	v_fmac_f32_e32 v241, v209, v65
	v_fmac_f32_e32 v242, v210, v66
	v_fmac_f32_e32 v243, v211, v67
	global_store_dwordx4 v244, v[228:231], s[52:53] offset:384
	global_store_dwordx4 v244, v[232:235], s[52:53] offset:416
	global_store_dwordx4 v244, v[236:239], s[52:53] offset:448
	global_store_dwordx4 v244, v[240:243], s[52:53] offset:480
	global_load_dwordx4 v[148:151], v246, s[54:55] offset:512
	global_load_dwordx4 v[152:155], v246, s[54:55] offset:544
	global_load_dwordx4 v[156:159], v246, s[54:55] offset:576
	global_load_dwordx4 v[160:163], v246, s[54:55] offset:608
	global_load_dwordx4 v[164:167], v246, s[54:55] offset:640
	global_load_dwordx4 v[168:171], v246, s[54:55] offset:672
	global_load_dwordx4 v[172:175], v246, s[54:55] offset:704
	global_load_dwordx4 v[176:179], v246, s[54:55] offset:736
	global_load_dwordx4 v[180:183], v246, s[54:55] offset:768
	global_load_dwordx4 v[184:187], v246, s[54:55] offset:800
	global_load_dwordx4 v[188:191], v246, s[54:55] offset:832
	global_load_dwordx4 v[192:195], v246, s[54:55] offset:864
	global_load_dwordx4 v[196:199], v246, s[54:55] offset:896
	global_load_dwordx4 v[200:203], v246, s[54:55] offset:928
	global_load_dwordx4 v[204:207], v246, s[54:55] offset:960
	global_load_dwordx4 v[208:211], v246, s[54:55] offset:992
	global_load_dwordx4 v[212:215], v244, s[52:53] offset:512
	global_load_dwordx4 v[216:219], v244, s[52:53] offset:544
	global_load_dwordx4 v[220:223], v244, s[52:53] offset:576
	global_load_dwordx4 v[224:227], v244, s[52:53] offset:608
	global_load_dwordx4 v[228:231], v244, s[52:53] offset:640
	global_load_dwordx4 v[232:235], v244, s[52:53] offset:672
	global_load_dwordx4 v[236:239], v244, s[52:53] offset:704
	global_load_dwordx4 v[240:243], v244, s[52:53] offset:736
	s_waitcnt vmcnt(4)
	v_fmac_f32_e32 v212, v148, v68
	v_fmac_f32_e32 v213, v149, v69
	v_fmac_f32_e32 v214, v150, v70
	v_fmac_f32_e32 v215, v151, v71
	v_fmac_f32_e32 v216, v152, v72
	v_fmac_f32_e32 v217, v153, v73
	v_fmac_f32_e32 v218, v154, v74
	v_fmac_f32_e32 v219, v155, v75
	v_fmac_f32_e32 v220, v156, v76
	v_fmac_f32_e32 v221, v157, v77
	v_fmac_f32_e32 v222, v158, v78
	v_fmac_f32_e32 v223, v159, v79
	v_fmac_f32_e32 v224, v160, v80
	v_fmac_f32_e32 v225, v161, v81
	v_fmac_f32_e32 v226, v162, v82
	v_fmac_f32_e32 v227, v163, v83
	global_store_dwordx4 v244, v[212:215], s[52:53] offset:512
	global_store_dwordx4 v244, v[216:219], s[52:53] offset:544
	global_store_dwordx4 v244, v[220:223], s[52:53] offset:576
	global_store_dwordx4 v244, v[224:227], s[52:53] offset:608
	global_load_dwordx4 v[212:215], v244, s[52:53] offset:768
	global_load_dwordx4 v[216:219], v244, s[52:53] offset:800
	global_load_dwordx4 v[220:223], v244, s[52:53] offset:832
	global_load_dwordx4 v[224:227], v244, s[52:53] offset:864
	s_waitcnt vmcnt(4)
	v_fmac_f32_e32 v228, v164, v84
	v_fmac_f32_e32 v229, v165, v85
	v_fmac_f32_e32 v230, v166, v86
	v_fmac_f32_e32 v231, v167, v87
	v_fmac_f32_e32 v232, v168, v88
	v_fmac_f32_e32 v233, v169, v89
	v_fmac_f32_e32 v234, v170, v90
	v_fmac_f32_e32 v235, v171, v91
	v_fmac_f32_e32 v236, v172, v92
	v_fmac_f32_e32 v237, v173, v93
	v_fmac_f32_e32 v238, v174, v94
	v_fmac_f32_e32 v239, v175, v95
	v_fmac_f32_e32 v240, v176, v96
	v_fmac_f32_e32 v241, v177, v97
	v_fmac_f32_e32 v242, v178, v98
	v_fmac_f32_e32 v243, v179, v99
	global_store_dwordx4 v244, v[228:231], s[52:53] offset:640
	global_store_dwordx4 v244, v[232:235], s[52:53] offset:672
	global_store_dwordx4 v244, v[236:239], s[52:53] offset:704
	global_store_dwordx4 v244, v[240:243], s[52:53] offset:736
	global_load_dwordx4 v[228:231], v244, s[52:53] offset:896
	global_load_dwordx4 v[232:235], v244, s[52:53] offset:928
	global_load_dwordx4 v[236:239], v244, s[52:53] offset:960
	global_load_dwordx4 v[240:243], v244, s[52:53] offset:992
	s_waitcnt vmcnt(4)
	v_fmac_f32_e32 v212, v180, v100
	v_fmac_f32_e32 v213, v181, v101
	v_fmac_f32_e32 v214, v182, v102
	v_fmac_f32_e32 v215, v183, v103
	v_fmac_f32_e32 v216, v184, v104
	v_fmac_f32_e32 v217, v185, v105
	v_fmac_f32_e32 v218, v186, v106
	v_fmac_f32_e32 v219, v187, v107
	v_fmac_f32_e32 v220, v188, v108
	v_fmac_f32_e32 v221, v189, v109
	v_fmac_f32_e32 v222, v190, v110
	v_fmac_f32_e32 v223, v191, v111
	v_fmac_f32_e32 v224, v192, v112
	v_fmac_f32_e32 v225, v193, v113
	v_fmac_f32_e32 v226, v194, v114
	v_fmac_f32_e32 v227, v195, v115
	global_store_dwordx4 v244, v[212:215], s[52:53] offset:768
	global_store_dwordx4 v244, v[216:219], s[52:53] offset:800
	global_store_dwordx4 v244, v[220:223], s[52:53] offset:832
	global_store_dwordx4 v244, v[224:227], s[52:53] offset:864
	s_waitcnt vmcnt(0)
	v_fmac_f32_e32 v228, v196, v116
	v_fmac_f32_e32 v229, v197, v117
	v_fmac_f32_e32 v230, v198, v118
	v_fmac_f32_e32 v231, v199, v119
	v_fmac_f32_e32 v232, v200, v120
	v_fmac_f32_e32 v233, v201, v121
	v_fmac_f32_e32 v234, v202, v122
	v_fmac_f32_e32 v235, v203, v123
	v_fmac_f32_e32 v236, v204, v124
	v_fmac_f32_e32 v237, v205, v125
	v_fmac_f32_e32 v238, v206, v126
	v_fmac_f32_e32 v239, v207, v127
	v_fmac_f32_e32 v240, v208, v128
	v_fmac_f32_e32 v241, v209, v129
	v_fmac_f32_e32 v242, v210, v130
	v_fmac_f32_e32 v243, v211, v131
	global_store_dwordx4 v244, v[228:231], s[52:53] offset:896
	global_store_dwordx4 v244, v[232:235], s[52:53] offset:928
	global_store_dwordx4 v244, v[236:239], s[52:53] offset:960
	global_store_dwordx4 v244, v[240:243], s[52:53] offset:992
